# EpiKVQG epilogue regenerated: loads upfront, one wait, 16 B lane-paired stores for k/v sections and q heads
# speedup vs baseline: 1.0103x; 1.0103x over previous
.LBB0_851:
	ds_read_b128 v[120:123], v172
	ds_read_b128 v[124:127], v172 offset:1024
	ds_read_b128 v[156:159], v172 offset:2048
	ds_read_b128 v[160:163], v172 offset:3072
	s_add_u32 s16, s14, 0xfff80080
	s_addc_u32 s17, s15, -1
	s_cmp_eq_u32 s84, 28
	s_cselect_b32 s83, s13, s17
	s_cselect_b32 s82, s45, s16
	s_cselect_b32 s17, s60, s81
	s_cselect_b32 s16, s73, s75
	v_lshl_add_u64 v[168:169], s[14:15], 0, v[148:149]
	s_add_i32 m0, s90, 0xc000
	ds_read_b128 v[164:167], v173
	ds_read_b128 v[178:181], v173 offset:1024
	ds_read_b128 v[182:185], v173 offset:2048
	ds_read_b128 v[186:189], v173 offset:3072
	ds_read_b128 v[190:193], v173 offset:4096
	ds_read_b128 v[194:197], v173 offset:5120
	ds_read_b128 v[198:201], v173 offset:6144
	ds_read_b128 v[202:205], v173 offset:7168
	global_load_lds_dwordx4 v[168:169], off
	v_lshl_add_u64 v[168:169], s[14:15], 0, v[150:151]
	s_add_i32 m0, s90, 0xe000
	s_nop 0
	global_load_lds_dwordx4 v[168:169], off
	s_waitcnt lgkmcnt(8)
	s_barrier
	s_waitcnt lgkmcnt(0)
	s_setprio 1
	s_waitcnt lgkmcnt(0)
	v_mfma_f32_16x16x32_bf16 v[132:135], v[120:123], v[164:167], v[132:135]
	v_mfma_f32_16x16x32_bf16 v[128:131], v[156:159], v[164:167], v[128:131]
	v_mfma_f32_16x16x32_bf16 v[108:111], v[120:123], v[182:185], v[108:111]
	v_mfma_f32_16x16x32_bf16 v[104:107], v[156:159], v[182:185], v[104:107]
	v_mfma_f32_16x16x32_bf16 v[92:95], v[120:123], v[190:193], v[92:95]
	v_mfma_f32_16x16x32_bf16 v[88:91], v[156:159], v[190:193], v[88:91]
	v_mfma_f32_16x16x32_bf16 v[76:79], v[120:123], v[198:201], v[76:79]
	v_mfma_f32_16x16x32_bf16 v[72:75], v[156:159], v[198:201], v[72:75]
	v_mfma_f32_16x16x32_bf16 v[132:135], v[124:127], v[178:181], v[132:135]
	v_mfma_f32_16x16x32_bf16 v[128:131], v[160:163], v[178:181], v[128:131]
	v_mfma_f32_16x16x32_bf16 v[108:111], v[124:127], v[186:189], v[108:111]
	v_mfma_f32_16x16x32_bf16 v[104:107], v[160:163], v[186:189], v[104:107]
	v_mfma_f32_16x16x32_bf16 v[92:95], v[124:127], v[194:197], v[92:95]
	v_mfma_f32_16x16x32_bf16 v[88:91], v[160:163], v[194:197], v[88:91]
	v_mfma_f32_16x16x32_bf16 v[76:79], v[124:127], v[202:205], v[76:79]
	v_mfma_f32_16x16x32_bf16 v[72:75], v[160:163], v[202:205], v[72:75]
	s_setprio 0
	s_barrier
	s_add_i32 s85, s6, s69
	v_lshl_add_u64 v[168:169], s[16:17], 0, v[138:139]
	s_mov_b32 m0, s85
	ds_read_b128 v[206:209], v174
	ds_read_b128 v[210:213], v174 offset:1024
	ds_read_b128 v[214:217], v174 offset:2048
	ds_read_b128 v[218:221], v174 offset:3072
	global_load_lds_dwordx4 v[168:169], off
	v_lshl_add_u64 v[222:223], s[16:17], 0, v[140:141]
	s_add_i32 m0, s85, 0x2000
	s_nop 0
	global_load_lds_dwordx4 v[222:223], off
	s_barrier
	s_waitcnt lgkmcnt(0)
	s_setprio 1
	s_waitcnt lgkmcnt(0)
	v_mfma_f32_16x16x32_bf16 v[116:119], v[206:209], v[164:167], v[116:119]
	v_mfma_f32_16x16x32_bf16 v[112:115], v[214:217], v[164:167], v[112:115]
	v_mfma_f32_16x16x32_bf16 v[100:103], v[206:209], v[182:185], v[100:103]
	v_mfma_f32_16x16x32_bf16 v[96:99], v[214:217], v[182:185], v[96:99]
	v_mfma_f32_16x16x32_bf16 v[84:87], v[206:209], v[190:193], v[84:87]
	v_mfma_f32_16x16x32_bf16 v[80:83], v[214:217], v[190:193], v[80:83]
	v_mfma_f32_16x16x32_bf16 v[68:71], v[206:209], v[198:201], v[68:71]
	v_mfma_f32_16x16x32_bf16 v[64:67], v[214:217], v[198:201], v[64:67]
	v_mfma_f32_16x16x32_bf16 v[116:119], v[210:213], v[178:181], v[116:119]
	v_mfma_f32_16x16x32_bf16 v[112:115], v[218:221], v[178:181], v[112:115]
	v_mfma_f32_16x16x32_bf16 v[100:103], v[210:213], v[186:189], v[100:103]
	v_mfma_f32_16x16x32_bf16 v[96:99], v[218:221], v[186:189], v[96:99]
	v_mfma_f32_16x16x32_bf16 v[84:87], v[210:213], v[194:197], v[84:87]
	v_mfma_f32_16x16x32_bf16 v[80:83], v[218:221], v[194:197], v[80:83]
	v_mfma_f32_16x16x32_bf16 v[68:71], v[210:213], v[202:205], v[68:71]
	v_mfma_f32_16x16x32_bf16 v[64:67], v[218:221], v[202:205], v[64:67]
	s_setprio 0
	s_mov_b32 m0, s90
	v_lshl_add_u64 v[224:225], s[82:83], 0, v[138:139]
	s_barrier
	ds_read_b128 v[164:167], v173 offset:16384
	ds_read_b128 v[178:181], v173 offset:17408
	ds_read_b128 v[182:185], v173 offset:18432
	ds_read_b128 v[186:189], v173 offset:19456
	ds_read_b128 v[190:193], v173 offset:20480
	ds_read_b128 v[194:197], v173 offset:21504
	ds_read_b128 v[198:201], v173 offset:22528
	ds_read_b128 v[202:205], v173 offset:23552
	global_load_lds_dwordx4 v[224:225], off
	v_lshl_add_u64 v[226:227], s[82:83], 0, v[140:141]
	s_mov_b32 m0, s91
	s_nop 0
	global_load_lds_dwordx4 v[226:227], off
	s_barrier
	s_waitcnt lgkmcnt(0)
	s_setprio 1
	s_waitcnt lgkmcnt(0)
	v_mfma_f32_16x16x32_bf16 v[60:63], v[120:123], v[164:167], v[60:63]
	v_mfma_f32_16x16x32_bf16 v[56:59], v[156:159], v[164:167], v[56:59]
	v_mfma_f32_16x16x32_bf16 v[44:47], v[120:123], v[182:185], v[44:47]
	v_mfma_f32_16x16x32_bf16 v[40:43], v[156:159], v[182:185], v[40:43]
	v_mfma_f32_16x16x32_bf16 v[28:31], v[120:123], v[190:193], v[28:31]
	v_mfma_f32_16x16x32_bf16 v[24:27], v[156:159], v[190:193], v[24:27]
	v_mfma_f32_16x16x32_bf16 v[12:15], v[120:123], v[198:201], v[12:15]
	v_mfma_f32_16x16x32_bf16 v[8:11], v[156:159], v[198:201], v[8:11]
	v_mfma_f32_16x16x32_bf16 v[60:63], v[124:127], v[178:181], v[60:63]
	v_mfma_f32_16x16x32_bf16 v[56:59], v[160:163], v[178:181], v[56:59]
	v_mfma_f32_16x16x32_bf16 v[44:47], v[124:127], v[186:189], v[44:47]
	v_mfma_f32_16x16x32_bf16 v[40:43], v[160:163], v[186:189], v[40:43]
	v_mfma_f32_16x16x32_bf16 v[28:31], v[124:127], v[194:197], v[28:31]
	v_mfma_f32_16x16x32_bf16 v[24:27], v[160:163], v[194:197], v[24:27]
	v_mfma_f32_16x16x32_bf16 v[12:15], v[124:127], v[202:205], v[12:15]
	v_mfma_f32_16x16x32_bf16 v[8:11], v[160:163], v[202:205], v[8:11]
	s_setprio 0
	s_barrier
	s_add_u32 s86, s16, 0x80000
	s_addc_u32 s87, s17, 0
	s_add_i32 s85, s7, s69
	v_lshl_add_u64 v[120:121], s[86:87], 0, v[138:139]
	s_mov_b32 m0, s85
	s_nop 0
	global_load_lds_dwordx4 v[120:121], off
	v_lshl_add_u64 v[120:121], s[86:87], 0, v[140:141]
	s_add_i32 m0, s85, 0x2000
	s_nop 0
	global_load_lds_dwordx4 v[120:121], off
	s_waitcnt vmcnt(6)
	s_barrier
	s_setprio 1
	v_mfma_f32_16x16x32_bf16 v[52:55], v[206:209], v[164:167], v[52:55]
	v_mfma_f32_16x16x32_bf16 v[48:51], v[214:217], v[164:167], v[48:51]
	v_mfma_f32_16x16x32_bf16 v[36:39], v[206:209], v[182:185], v[36:39]
	v_mfma_f32_16x16x32_bf16 v[32:35], v[214:217], v[182:185], v[32:35]
	v_mfma_f32_16x16x32_bf16 v[20:23], v[206:209], v[190:193], v[20:23]
	v_mfma_f32_16x16x32_bf16 v[16:19], v[214:217], v[190:193], v[16:19]
	v_mfma_f32_16x16x32_bf16 v[4:7], v[206:209], v[198:201], v[4:7]
	v_mfma_f32_16x16x32_bf16 v[0:3], v[214:217], v[198:201], v[0:3]
	v_mfma_f32_16x16x32_bf16 v[52:55], v[210:213], v[178:181], v[52:55]
	v_mfma_f32_16x16x32_bf16 v[48:51], v[218:221], v[178:181], v[48:51]
	v_mfma_f32_16x16x32_bf16 v[36:39], v[210:213], v[186:189], v[36:39]
	v_mfma_f32_16x16x32_bf16 v[32:35], v[218:221], v[186:189], v[32:35]
	v_mfma_f32_16x16x32_bf16 v[20:23], v[210:213], v[194:197], v[20:23]
	v_mfma_f32_16x16x32_bf16 v[16:19], v[218:221], v[194:197], v[16:19]
	v_mfma_f32_16x16x32_bf16 v[4:7], v[210:213], v[202:205], v[4:7]
	v_mfma_f32_16x16x32_bf16 v[0:3], v[218:221], v[202:205], v[0:3]
	s_setprio 0
	s_add_i32 s85, 16, 0x18000
	v_add_u32_e32 v142, s85, v171
	s_barrier
	ds_read_b128 v[120:123], v142
	ds_read_b128 v[124:127], v142 offset:1024
	ds_read_b128 v[156:159], v142 offset:2048
	ds_read_b128 v[160:163], v142 offset:3072
	s_add_u32 s82, s82, 0x80000
	s_addc_u32 s83, s83, 0
	s_mov_b32 m0, s54
	v_lshl_add_u64 v[206:207], s[82:83], 0, v[138:139]
	ds_read_b128 v[164:167], v173 offset:32768
	ds_read_b128 v[178:181], v173 offset:33792
	ds_read_b128 v[182:185], v173 offset:34816
	ds_read_b128 v[186:189], v173 offset:35840
	ds_read_b128 v[190:193], v173 offset:36864
	ds_read_b128 v[194:197], v173 offset:37888
	ds_read_b128 v[198:201], v173 offset:38912
	ds_read_b128 v[202:205], v173 offset:39936
	global_load_lds_dwordx4 v[206:207], off
	v_lshl_add_u64 v[206:207], s[82:83], 0, v[140:141]
	s_mov_b32 m0, s55
	s_nop 0
	global_load_lds_dwordx4 v[206:207], off
	s_waitcnt lgkmcnt(8)
	s_barrier
	s_waitcnt lgkmcnt(0)
	s_setprio 1
	s_waitcnt lgkmcnt(0)
	v_mfma_f32_16x16x32_bf16 v[132:135], v[120:123], v[164:167], v[132:135]
	v_mfma_f32_16x16x32_bf16 v[128:131], v[156:159], v[164:167], v[128:131]
	v_mfma_f32_16x16x32_bf16 v[108:111], v[120:123], v[182:185], v[108:111]
	v_mfma_f32_16x16x32_bf16 v[104:107], v[156:159], v[182:185], v[104:107]
	v_mfma_f32_16x16x32_bf16 v[92:95], v[120:123], v[190:193], v[92:95]
	v_mfma_f32_16x16x32_bf16 v[88:91], v[156:159], v[190:193], v[88:91]
	v_mfma_f32_16x16x32_bf16 v[76:79], v[120:123], v[198:201], v[76:79]
	v_mfma_f32_16x16x32_bf16 v[72:75], v[156:159], v[198:201], v[72:75]
	v_mfma_f32_16x16x32_bf16 v[132:135], v[124:127], v[178:181], v[132:135]
	v_mfma_f32_16x16x32_bf16 v[128:131], v[160:163], v[178:181], v[128:131]
	v_mfma_f32_16x16x32_bf16 v[108:111], v[124:127], v[186:189], v[108:111]
	v_mfma_f32_16x16x32_bf16 v[104:107], v[160:163], v[186:189], v[104:107]
	v_mfma_f32_16x16x32_bf16 v[92:95], v[124:127], v[194:197], v[92:95]
	v_mfma_f32_16x16x32_bf16 v[88:91], v[160:163], v[194:197], v[88:91]
	v_mfma_f32_16x16x32_bf16 v[76:79], v[124:127], v[202:205], v[76:79]
	v_mfma_f32_16x16x32_bf16 v[72:75], v[160:163], v[202:205], v[72:75]
	s_setprio 0
	s_barrier
	s_add_i32 s82, 16, 0x1c000
	s_add_i32 s83, s85, s69
	v_add_u32_e32 v142, s82, v171
	v_lshl_add_u64 v[168:169], v[168:169], 0, s[20:21]
	s_mov_b32 m0, s83
	ds_read_b128 v[206:209], v142
	ds_read_b128 v[210:213], v142 offset:1024
	ds_read_b128 v[214:217], v142 offset:2048
	ds_read_b128 v[218:221], v142 offset:3072
	global_load_lds_dwordx4 v[168:169], off
	v_lshl_add_u64 v[168:169], v[222:223], 0, s[20:21]
	s_add_i32 m0, s83, 0x2000
	s_nop 0
	global_load_lds_dwordx4 v[168:169], off
	s_barrier
	s_waitcnt lgkmcnt(0)
	s_setprio 1
	s_waitcnt lgkmcnt(0)
	v_mfma_f32_16x16x32_bf16 v[116:119], v[206:209], v[164:167], v[116:119]
	v_mfma_f32_16x16x32_bf16 v[112:115], v[214:217], v[164:167], v[112:115]
	v_mfma_f32_16x16x32_bf16 v[100:103], v[206:209], v[182:185], v[100:103]
	v_mfma_f32_16x16x32_bf16 v[96:99], v[214:217], v[182:185], v[96:99]
	v_mfma_f32_16x16x32_bf16 v[84:87], v[206:209], v[190:193], v[84:87]
	v_mfma_f32_16x16x32_bf16 v[80:83], v[214:217], v[190:193], v[80:83]
	v_mfma_f32_16x16x32_bf16 v[68:71], v[206:209], v[198:201], v[68:71]
	v_mfma_f32_16x16x32_bf16 v[64:67], v[214:217], v[198:201], v[64:67]
	v_mfma_f32_16x16x32_bf16 v[116:119], v[210:213], v[178:181], v[116:119]
	v_mfma_f32_16x16x32_bf16 v[112:115], v[218:221], v[178:181], v[112:115]
	v_mfma_f32_16x16x32_bf16 v[100:103], v[210:213], v[186:189], v[100:103]
	v_mfma_f32_16x16x32_bf16 v[96:99], v[218:221], v[186:189], v[96:99]
	v_mfma_f32_16x16x32_bf16 v[84:87], v[210:213], v[194:197], v[84:87]
	v_mfma_f32_16x16x32_bf16 v[80:83], v[218:221], v[194:197], v[80:83]
	v_mfma_f32_16x16x32_bf16 v[68:71], v[210:213], v[202:205], v[68:71]
	v_mfma_f32_16x16x32_bf16 v[64:67], v[218:221], v[202:205], v[64:67]
	s_setprio 0
	s_mov_b32 m0, s8
	v_lshl_add_u64 v[168:169], v[224:225], 0, s[20:21]
	s_barrier
	ds_read_b128 v[164:167], v173 offset:49152
	ds_read_b128 v[178:181], v173 offset:50176
	ds_read_b128 v[182:185], v173 offset:51200
	ds_read_b128 v[186:189], v173 offset:52224
	ds_read_b128 v[190:193], v173 offset:53248
	ds_read_b128 v[194:197], v173 offset:54272
	ds_read_b128 v[198:201], v173 offset:55296
	ds_read_b128 v[202:205], v173 offset:56320
	global_load_lds_dwordx4 v[168:169], off
	v_lshl_add_u64 v[168:169], v[226:227], 0, s[20:21]
	s_mov_b32 m0, s9
	s_nop 0
	global_load_lds_dwordx4 v[168:169], off
	s_barrier
	s_waitcnt lgkmcnt(0)
	s_setprio 1
	s_waitcnt lgkmcnt(0)
	v_mfma_f32_16x16x32_bf16 v[60:63], v[120:123], v[164:167], v[60:63]
	v_mfma_f32_16x16x32_bf16 v[56:59], v[156:159], v[164:167], v[56:59]
	v_mfma_f32_16x16x32_bf16 v[44:47], v[120:123], v[182:185], v[44:47]
	v_mfma_f32_16x16x32_bf16 v[40:43], v[156:159], v[182:185], v[40:43]
	v_mfma_f32_16x16x32_bf16 v[28:31], v[120:123], v[190:193], v[28:31]
	v_mfma_f32_16x16x32_bf16 v[24:27], v[156:159], v[190:193], v[24:27]
	v_mfma_f32_16x16x32_bf16 v[12:15], v[120:123], v[198:201], v[12:15]
	v_mfma_f32_16x16x32_bf16 v[8:11], v[156:159], v[198:201], v[8:11]
	v_mfma_f32_16x16x32_bf16 v[60:63], v[124:127], v[178:181], v[60:63]
	v_mfma_f32_16x16x32_bf16 v[56:59], v[160:163], v[178:181], v[56:59]
	v_mfma_f32_16x16x32_bf16 v[44:47], v[124:127], v[186:189], v[44:47]
	v_mfma_f32_16x16x32_bf16 v[40:43], v[160:163], v[186:189], v[40:43]
	v_mfma_f32_16x16x32_bf16 v[28:31], v[124:127], v[194:197], v[28:31]
	v_mfma_f32_16x16x32_bf16 v[24:27], v[160:163], v[194:197], v[24:27]
	v_mfma_f32_16x16x32_bf16 v[12:15], v[124:127], v[202:205], v[12:15]
	v_mfma_f32_16x16x32_bf16 v[8:11], v[160:163], v[202:205], v[8:11]
	s_setprio 0
	s_barrier
	s_add_u32 s16, s16, 0x80080
	s_addc_u32 s17, s17, 0
	s_add_i32 s82, s82, s69
	v_lshl_add_u64 v[120:121], s[16:17], 0, v[138:139]
	s_mov_b32 m0, s82
	s_nop 0
	global_load_lds_dwordx4 v[120:121], off
	v_lshl_add_u64 v[120:121], s[16:17], 0, v[140:141]
	s_add_i32 m0, s82, 0x2000
	s_nop 0
	global_load_lds_dwordx4 v[120:121], off
	s_waitcnt vmcnt(6)
	s_barrier
	s_setprio 1
	v_mfma_f32_16x16x32_bf16 v[52:55], v[206:209], v[164:167], v[52:55]
	v_mfma_f32_16x16x32_bf16 v[48:51], v[214:217], v[164:167], v[48:51]
	v_mfma_f32_16x16x32_bf16 v[36:39], v[206:209], v[182:185], v[36:39]
	v_mfma_f32_16x16x32_bf16 v[32:35], v[214:217], v[182:185], v[32:35]
	v_mfma_f32_16x16x32_bf16 v[20:23], v[206:209], v[190:193], v[20:23]
	v_mfma_f32_16x16x32_bf16 v[16:19], v[214:217], v[190:193], v[16:19]
	v_mfma_f32_16x16x32_bf16 v[4:7], v[206:209], v[198:201], v[4:7]
	v_mfma_f32_16x16x32_bf16 v[0:3], v[214:217], v[198:201], v[0:3]
	v_mfma_f32_16x16x32_bf16 v[52:55], v[210:213], v[178:181], v[52:55]
	v_mfma_f32_16x16x32_bf16 v[48:51], v[218:221], v[178:181], v[48:51]
	v_mfma_f32_16x16x32_bf16 v[36:39], v[210:213], v[186:189], v[36:39]
	v_mfma_f32_16x16x32_bf16 v[32:35], v[218:221], v[186:189], v[32:35]
	v_mfma_f32_16x16x32_bf16 v[20:23], v[210:213], v[194:197], v[20:23]
	v_mfma_f32_16x16x32_bf16 v[16:19], v[218:221], v[194:197], v[16:19]
	v_mfma_f32_16x16x32_bf16 v[4:7], v[210:213], v[202:205], v[4:7]
	v_mfma_f32_16x16x32_bf16 v[0:3], v[218:221], v[202:205], v[0:3]
	s_setprio 0
	s_add_i32 s84, s84, 2
	s_add_u32 s14, s14, 0x100
	s_addc_u32 s15, s15, 0
	s_add_u32 s75, s75, 0x100
	s_addc_u32 s81, s81, 0
	s_cmp_gt_u32 s84, 29
	s_barrier
	s_cbranch_scc0 .LBB0_851
	s_lshl_b32 s75, s12, 8
	s_add_i32 s75, s75, s46
	v_or_b32_e32 v168, s75, v145
	v_ashrrev_i32_e32 v169, 31, v168
	v_lshl_add_u64 v[226:227], v[168:169], 2, s[22:23]
	global_load_dword v156, v[226:227], off offset:0
	global_load_dword v157, v[226:227], off offset:64
	global_load_dword v158, v[226:227], off offset:128
	global_load_dword v159, v[226:227], off offset:192
	global_load_dword v160, v[226:227], off offset:512
	global_load_dword v161, v[226:227], off offset:576
	global_load_dword v162, v[226:227], off offset:640
	global_load_dword v163, v[226:227], off offset:704
	s_cmp_gt_i32 s80, 11
	s_cselect_b64 s[16:17], -1, 0
	s_cselect_b32 s13, s68, 1.0
	v_mov_b32_e32 v236, s13
	s_ashr_i32 s84, s80, 1
	s_mov_b32 s85, 0
	s_cmp_eq_u32 s84, 2
	s_cselect_b64 s[82:83], -1, 0
	s_cmp_eq_u32 s84, 4
	s_cselect_b64 s[86:87], -1, 0
	s_or_b64 s[82:83], s[82:83], s[86:87]
	s_or_b64 s[82:83], s[82:83], s[16:17]
	s_and_b64 s[14:15], s[82:83], s[62:63]
	v_lshlrev_b32_e32 v142, 1, v144
	v_and_b32_e32 v233, 8, v142
	v_mad_u32_u24 v142, v233, 3, v142
	v_and_b32_e32 v233, 0x1fff, v168
	v_lshlrev_b32_e32 v238, 7, v233
	v_lshl_or_b32 v238, v170, 2, v238
	s_and_b64 vcc, exec, s[16:17]
	s_cbranch_vccnz .Lkq_q
	s_lshl_b64 s[86:87], s[84:85], 24
	s_add_u32 s86, s50, s86
	s_addc_u32 s87, s51, s87
	s_lshr_b32 s45, s75, 13
	s_lshl_b32 s45, s45, 2
	s_and_b32 s60, s80, 1
	s_lshl_b32 s60, s60, 1
	s_or_b32 s45, s45, s60
	v_lshl_or_b32 v226, s45, 13, v233
	v_mov_b32_e32 v227, 0
	v_lshlrev_b64 v[226:227], 8, v[226:227]
	v_lshl_add_u64 v[226:227], s[86:87], 0, v[226:227]
	s_mov_b32 s88, 0x200000
	s_mov_b32 s82, 0x1000
	s_mov_b32 s86, 0x5000
	s_branch .Lkq_addr
.Lkq_q:
	v_lshlrev_b64 v[226:227], 12, v[168:169]
	v_lshl_add_u64 v[226:227], s[18:19], 0, v[226:227]
	s_sub_i32 s86, s80, 12
	s_lshl_b32 s86, s86, 9
	s_mov_b32 s87, 0
	v_lshl_add_u64 v[226:227], v[226:227], 0, s[86:87]
	s_mov_b32 s88, 0x100
	s_mov_b32 s82, 0x10000
	s_mov_b32 s86, 0x50000
.Lkq_addr:
	s_mov_b32 s89, 0
	s_mov_b32 s83, 0
	s_mov_b32 s87, 0
	s_lshl_b32 s84, s47, 1
	s_mov_b32 s85, 0
	v_lshl_add_u64 v[226:227], v[226:227], 0, s[84:85]
	v_lshl_add_u64 v[226:227], v[226:227], 0, v[142:143]
	s_and_b64 vcc, exec, s[14:15]
	s_cbranch_vccz .Lkq_noropeld
	v_add_u32_e32 v239, 0x1000, v238
	v_add_u32_e32 v233, 0x4000, v238
	v_add_u32_e32 v142, 0x5000, v238
	global_load_dwordx4 v[178:181], v238, s[58:59] offset:0
	global_load_dwordx4 v[182:185], v238, s[58:59] offset:16
	global_load_dwordx4 v[186:189], v238, s[58:59] offset:2048
	global_load_dwordx4 v[190:193], v238, s[58:59] offset:2064
	global_load_dwordx4 v[194:197], v239, s[58:59] offset:0
	global_load_dwordx4 v[198:201], v239, s[58:59] offset:16
	global_load_dwordx4 v[202:205], v239, s[58:59] offset:2048
	global_load_dwordx4 v[206:209], v239, s[58:59] offset:2064
	global_load_dwordx4 v[210:213], v233, s[58:59] offset:0
	global_load_dwordx4 v[214:217], v233, s[58:59] offset:16
	global_load_dwordx4 v[218:221], v233, s[58:59] offset:2048
	global_load_dwordx4 v[120:123], v233, s[58:59] offset:2064
	global_load_dwordx4 v[124:127], v142, s[58:59] offset:0
	global_load_dwordx4 v[164:167], v142, s[58:59] offset:16
	global_load_dwordx4 v[222:225], v142, s[58:59] offset:2048
	global_load_dwordx4 v[228:231], v142, s[58:59] offset:2064
.Lkq_noropeld:
	s_waitcnt vmcnt(0)
	v_fmamk_f32 v156, v156, 0x3a000000, v175
	v_fmamk_f32 v157, v157, 0x3a000000, v175
	v_fmamk_f32 v158, v158, 0x3a000000, v175
	v_fmamk_f32 v159, v159, 0x3a000000, v175
	v_fmamk_f32 v160, v160, 0x3a000000, v175
	v_fmamk_f32 v161, v161, 0x3a000000, v175
	v_fmamk_f32 v162, v162, 0x3a000000, v175
	v_fmamk_f32 v163, v163, 0x3a000000, v175
	v_mul_f32_e32 v239, 0x4b800000, v156
	v_cmp_gt_f32_e32 vcc, s39, v156
	s_nop 1
	v_cndmask_b32_e32 v156, v156, v239, vcc
	v_rsq_f32_e32 v156, v156
	s_nop 0
	v_mul_f32_e32 v239, 0x45800000, v156
	v_cndmask_b32_e32 v156, v156, v239, vcc
	v_mul_f32_e32 v238, 0x4b800000, v157
	v_cmp_gt_f32_e32 vcc, s39, v157
	s_nop 1
	v_cndmask_b32_e32 v157, v157, v238, vcc
	v_rsq_f32_e32 v157, v157
	s_nop 0
	v_mul_f32_e32 v238, 0x45800000, v157
	v_cndmask_b32_e32 v157, v157, v238, vcc
	v_mul_f32_e32 v239, 0x4b800000, v158
	v_cmp_gt_f32_e32 vcc, s39, v158
	s_nop 1
	v_cndmask_b32_e32 v158, v158, v239, vcc
	v_rsq_f32_e32 v158, v158
	s_nop 0
	v_mul_f32_e32 v239, 0x45800000, v158
	v_cndmask_b32_e32 v158, v158, v239, vcc
	v_mul_f32_e32 v238, 0x4b800000, v159
	v_cmp_gt_f32_e32 vcc, s39, v159
	s_nop 1
	v_cndmask_b32_e32 v159, v159, v238, vcc
	v_rsq_f32_e32 v159, v159
	s_nop 0
	v_mul_f32_e32 v238, 0x45800000, v159
	v_cndmask_b32_e32 v159, v159, v238, vcc
	v_mul_f32_e32 v239, 0x4b800000, v160
	v_cmp_gt_f32_e32 vcc, s39, v160
	s_nop 1
	v_cndmask_b32_e32 v160, v160, v239, vcc
	v_rsq_f32_e32 v160, v160
	s_nop 0
	v_mul_f32_e32 v239, 0x45800000, v160
	v_cndmask_b32_e32 v160, v160, v239, vcc
	v_mul_f32_e32 v238, 0x4b800000, v161
	v_cmp_gt_f32_e32 vcc, s39, v161
	s_nop 1
	v_cndmask_b32_e32 v161, v161, v238, vcc
	v_rsq_f32_e32 v161, v161
	s_nop 0
	v_mul_f32_e32 v238, 0x45800000, v161
	v_cndmask_b32_e32 v161, v161, v238, vcc
	v_mul_f32_e32 v239, 0x4b800000, v162
	v_cmp_gt_f32_e32 vcc, s39, v162
	s_nop 1
	v_cndmask_b32_e32 v162, v162, v239, vcc
	v_rsq_f32_e32 v162, v162
	s_nop 0
	v_mul_f32_e32 v239, 0x45800000, v162
	v_cndmask_b32_e32 v162, v162, v239, vcc
	v_mul_f32_e32 v238, 0x4b800000, v163
	v_cmp_gt_f32_e32 vcc, s39, v163
	s_nop 1
	v_cndmask_b32_e32 v163, v163, v238, vcc
	v_rsq_f32_e32 v163, v163
	s_nop 0
	v_mul_f32_e32 v238, 0x45800000, v163
	v_cndmask_b32_e32 v163, v163, v238, vcc
	v_lshl_add_u64 v[234:235], v[226:227], 0, s[88:89]
	v_pk_mul_f32 v[132:133], v[132:133], v[156:157] op_sel:[0,0] op_sel_hi:[1,0]
	v_pk_mul_f32 v[134:135], v[134:135], v[156:157] op_sel:[0,0] op_sel_hi:[1,0]
	v_pk_mul_f32 v[128:129], v[128:129], v[156:157] op_sel:[0,0] op_sel_hi:[1,0]
	v_pk_mul_f32 v[130:131], v[130:131], v[156:157] op_sel:[0,0] op_sel_hi:[1,0]
	v_pk_mul_f32 v[116:117], v[116:117], v[156:157] op_sel:[0,0] op_sel_hi:[1,0]
	v_pk_mul_f32 v[118:119], v[118:119], v[156:157] op_sel:[0,0] op_sel_hi:[1,0]
	v_pk_mul_f32 v[112:113], v[112:113], v[156:157] op_sel:[0,0] op_sel_hi:[1,0]
	v_pk_mul_f32 v[114:115], v[114:115], v[156:157] op_sel:[0,0] op_sel_hi:[1,0]
	s_and_b64 vcc, exec, s[14:15]
	s_cbranch_vccz .Lkq_norope_0
	v_mul_f32_e32 v142, v128, v179
	v_mul_f32_e32 v233, v132, v179
	v_fma_f32 v132, v132, v178, -v142
	v_fma_f32 v128, v128, v178, v233
	v_mul_f32_e32 v238, v129, v181
	v_mul_f32_e32 v239, v133, v181
	v_fma_f32 v133, v133, v180, -v238
	v_fma_f32 v129, v129, v180, v239
	v_mul_f32_e32 v142, v130, v183
	v_mul_f32_e32 v233, v134, v183
	v_fma_f32 v134, v134, v182, -v142
	v_fma_f32 v130, v130, v182, v233
	v_mul_f32_e32 v238, v131, v185
	v_mul_f32_e32 v239, v135, v185
	v_fma_f32 v135, v135, v184, -v238
	v_fma_f32 v131, v131, v184, v239
	v_mul_f32_e32 v142, v112, v179
	v_mul_f32_e32 v233, v116, v179
	v_fma_f32 v116, v116, v178, -v142
	v_fma_f32 v112, v112, v178, v233
	v_mul_f32_e32 v238, v113, v181
	v_mul_f32_e32 v239, v117, v181
	v_fma_f32 v117, v117, v180, -v238
	v_fma_f32 v113, v113, v180, v239
	v_mul_f32_e32 v142, v114, v183
	v_mul_f32_e32 v233, v118, v183
	v_fma_f32 v118, v118, v182, -v142
	v_fma_f32 v114, v114, v182, v233
	v_mul_f32_e32 v238, v115, v185
	v_mul_f32_e32 v239, v119, v185
	v_fma_f32 v119, v119, v184, -v238
	v_fma_f32 v115, v115, v184, v239
.Lkq_norope_0:
	v_pk_mul_f32 v[132:133], v[132:133], v[236:237] op_sel_hi:[1,0]
	v_pk_mul_f32 v[134:135], v[134:135], v[236:237] op_sel_hi:[1,0]
	v_pk_mul_f32 v[128:129], v[128:129], v[236:237] op_sel_hi:[1,0]
	v_pk_mul_f32 v[130:131], v[130:131], v[236:237] op_sel_hi:[1,0]
	v_pk_mul_f32 v[116:117], v[116:117], v[236:237] op_sel_hi:[1,0]
	v_pk_mul_f32 v[118:119], v[118:119], v[236:237] op_sel_hi:[1,0]
	v_pk_mul_f32 v[112:113], v[112:113], v[236:237] op_sel_hi:[1,0]
	v_pk_mul_f32 v[114:115], v[114:115], v[236:237] op_sel_hi:[1,0]
	v_cvt_pk_bf16_f32 v132, v132, v133
	v_cvt_pk_bf16_f32 v133, v134, v135
	v_cvt_pk_bf16_f32 v134, v128, v129
	v_cvt_pk_bf16_f32 v135, v130, v131
	v_cvt_pk_bf16_f32 v116, v116, v117
	v_cvt_pk_bf16_f32 v117, v118, v119
	v_cvt_pk_bf16_f32 v118, v112, v113
	v_cvt_pk_bf16_f32 v119, v114, v115
	s_nop 1
	v_permlane16_swap_b32_e32 v132, v134
	v_permlane16_swap_b32_e32 v133, v135
	v_permlane16_swap_b32_e32 v116, v118
	v_permlane16_swap_b32_e32 v117, v119
	global_store_dwordx4 v[226:227], v[132:135], off
	global_store_dwordx4 v[234:235], v[116:119], off
	v_lshl_add_u64 v[226:227], v[226:227], 0, s[82:83]
	v_lshl_add_u64 v[234:235], v[226:227], 0, s[88:89]
	v_pk_mul_f32 v[108:109], v[108:109], v[156:157] op_sel:[0,1] op_sel_hi:[1,1]
	v_pk_mul_f32 v[110:111], v[110:111], v[156:157] op_sel:[0,1] op_sel_hi:[1,1]
	v_pk_mul_f32 v[104:105], v[104:105], v[156:157] op_sel:[0,1] op_sel_hi:[1,1]
	v_pk_mul_f32 v[106:107], v[106:107], v[156:157] op_sel:[0,1] op_sel_hi:[1,1]
	v_pk_mul_f32 v[100:101], v[100:101], v[156:157] op_sel:[0,1] op_sel_hi:[1,1]
	v_pk_mul_f32 v[102:103], v[102:103], v[156:157] op_sel:[0,1] op_sel_hi:[1,1]
	v_pk_mul_f32 v[96:97], v[96:97], v[156:157] op_sel:[0,1] op_sel_hi:[1,1]
	v_pk_mul_f32 v[98:99], v[98:99], v[156:157] op_sel:[0,1] op_sel_hi:[1,1]
	s_and_b64 vcc, exec, s[14:15]
	s_cbranch_vccz .Lkq_norope_1
	v_mul_f32_e32 v142, v104, v187
	v_mul_f32_e32 v233, v108, v187
	v_fma_f32 v108, v108, v186, -v142
	v_fma_f32 v104, v104, v186, v233
	v_mul_f32_e32 v238, v105, v189
	v_mul_f32_e32 v239, v109, v189
	v_fma_f32 v109, v109, v188, -v238
	v_fma_f32 v105, v105, v188, v239
	v_mul_f32_e32 v142, v106, v191
	v_mul_f32_e32 v233, v110, v191
	v_fma_f32 v110, v110, v190, -v142
	v_fma_f32 v106, v106, v190, v233
	v_mul_f32_e32 v238, v107, v193
	v_mul_f32_e32 v239, v111, v193
	v_fma_f32 v111, v111, v192, -v238
	v_fma_f32 v107, v107, v192, v239
	v_mul_f32_e32 v142, v96, v187
	v_mul_f32_e32 v233, v100, v187
	v_fma_f32 v100, v100, v186, -v142
	v_fma_f32 v96, v96, v186, v233
	v_mul_f32_e32 v238, v97, v189
	v_mul_f32_e32 v239, v101, v189
	v_fma_f32 v101, v101, v188, -v238
	v_fma_f32 v97, v97, v188, v239
	v_mul_f32_e32 v142, v98, v191
	v_mul_f32_e32 v233, v102, v191
	v_fma_f32 v102, v102, v190, -v142
	v_fma_f32 v98, v98, v190, v233
	v_mul_f32_e32 v238, v99, v193
	v_mul_f32_e32 v239, v103, v193
	v_fma_f32 v103, v103, v192, -v238
	v_fma_f32 v99, v99, v192, v239
.Lkq_norope_1:
	v_pk_mul_f32 v[108:109], v[108:109], v[236:237] op_sel_hi:[1,0]
	v_pk_mul_f32 v[110:111], v[110:111], v[236:237] op_sel_hi:[1,0]
	v_pk_mul_f32 v[104:105], v[104:105], v[236:237] op_sel_hi:[1,0]
	v_pk_mul_f32 v[106:107], v[106:107], v[236:237] op_sel_hi:[1,0]
	v_pk_mul_f32 v[100:101], v[100:101], v[236:237] op_sel_hi:[1,0]
	v_pk_mul_f32 v[102:103], v[102:103], v[236:237] op_sel_hi:[1,0]
	v_pk_mul_f32 v[96:97], v[96:97], v[236:237] op_sel_hi:[1,0]
	v_pk_mul_f32 v[98:99], v[98:99], v[236:237] op_sel_hi:[1,0]
	v_cvt_pk_bf16_f32 v108, v108, v109
	v_cvt_pk_bf16_f32 v109, v110, v111
	v_cvt_pk_bf16_f32 v110, v104, v105
	v_cvt_pk_bf16_f32 v111, v106, v107
	v_cvt_pk_bf16_f32 v100, v100, v101
	v_cvt_pk_bf16_f32 v101, v102, v103
	v_cvt_pk_bf16_f32 v102, v96, v97
	v_cvt_pk_bf16_f32 v103, v98, v99
	s_nop 1
	v_permlane16_swap_b32_e32 v108, v110
	v_permlane16_swap_b32_e32 v109, v111
	v_permlane16_swap_b32_e32 v100, v102
	v_permlane16_swap_b32_e32 v101, v103
	global_store_dwordx4 v[226:227], v[108:111], off
	global_store_dwordx4 v[234:235], v[100:103], off
	v_lshl_add_u64 v[226:227], v[226:227], 0, s[82:83]
	v_lshl_add_u64 v[234:235], v[226:227], 0, s[88:89]
	v_pk_mul_f32 v[92:93], v[92:93], v[158:159] op_sel:[0,0] op_sel_hi:[1,0]
	v_pk_mul_f32 v[94:95], v[94:95], v[158:159] op_sel:[0,0] op_sel_hi:[1,0]
	v_pk_mul_f32 v[88:89], v[88:89], v[158:159] op_sel:[0,0] op_sel_hi:[1,0]
	v_pk_mul_f32 v[90:91], v[90:91], v[158:159] op_sel:[0,0] op_sel_hi:[1,0]
	v_pk_mul_f32 v[84:85], v[84:85], v[158:159] op_sel:[0,0] op_sel_hi:[1,0]
	v_pk_mul_f32 v[86:87], v[86:87], v[158:159] op_sel:[0,0] op_sel_hi:[1,0]
	v_pk_mul_f32 v[80:81], v[80:81], v[158:159] op_sel:[0,0] op_sel_hi:[1,0]
	v_pk_mul_f32 v[82:83], v[82:83], v[158:159] op_sel:[0,0] op_sel_hi:[1,0]
	s_and_b64 vcc, exec, s[14:15]
	s_cbranch_vccz .Lkq_norope_2
	v_mul_f32_e32 v142, v88, v195
	v_mul_f32_e32 v233, v92, v195
	v_fma_f32 v92, v92, v194, -v142
	v_fma_f32 v88, v88, v194, v233
	v_mul_f32_e32 v238, v89, v197
	v_mul_f32_e32 v239, v93, v197
	v_fma_f32 v93, v93, v196, -v238
	v_fma_f32 v89, v89, v196, v239
	v_mul_f32_e32 v142, v90, v199
	v_mul_f32_e32 v233, v94, v199
	v_fma_f32 v94, v94, v198, -v142
	v_fma_f32 v90, v90, v198, v233
	v_mul_f32_e32 v238, v91, v201
	v_mul_f32_e32 v239, v95, v201
	v_fma_f32 v95, v95, v200, -v238
	v_fma_f32 v91, v91, v200, v239
	v_mul_f32_e32 v142, v80, v195
	v_mul_f32_e32 v233, v84, v195
	v_fma_f32 v84, v84, v194, -v142
	v_fma_f32 v80, v80, v194, v233
	v_mul_f32_e32 v238, v81, v197
	v_mul_f32_e32 v239, v85, v197
	v_fma_f32 v85, v85, v196, -v238
	v_fma_f32 v81, v81, v196, v239
	v_mul_f32_e32 v142, v82, v199
	v_mul_f32_e32 v233, v86, v199
	v_fma_f32 v86, v86, v198, -v142
	v_fma_f32 v82, v82, v198, v233
	v_mul_f32_e32 v238, v83, v201
	v_mul_f32_e32 v239, v87, v201
	v_fma_f32 v87, v87, v200, -v238
	v_fma_f32 v83, v83, v200, v239
.Lkq_norope_2:
	v_pk_mul_f32 v[92:93], v[92:93], v[236:237] op_sel_hi:[1,0]
	v_pk_mul_f32 v[94:95], v[94:95], v[236:237] op_sel_hi:[1,0]
	v_pk_mul_f32 v[88:89], v[88:89], v[236:237] op_sel_hi:[1,0]
	v_pk_mul_f32 v[90:91], v[90:91], v[236:237] op_sel_hi:[1,0]
	v_pk_mul_f32 v[84:85], v[84:85], v[236:237] op_sel_hi:[1,0]
	v_pk_mul_f32 v[86:87], v[86:87], v[236:237] op_sel_hi:[1,0]
	v_pk_mul_f32 v[80:81], v[80:81], v[236:237] op_sel_hi:[1,0]
	v_pk_mul_f32 v[82:83], v[82:83], v[236:237] op_sel_hi:[1,0]
	v_cvt_pk_bf16_f32 v92, v92, v93
	v_cvt_pk_bf16_f32 v93, v94, v95
	v_cvt_pk_bf16_f32 v94, v88, v89
	v_cvt_pk_bf16_f32 v95, v90, v91
	v_cvt_pk_bf16_f32 v84, v84, v85
	v_cvt_pk_bf16_f32 v85, v86, v87
	v_cvt_pk_bf16_f32 v86, v80, v81
	v_cvt_pk_bf16_f32 v87, v82, v83
	s_nop 1
	v_permlane16_swap_b32_e32 v92, v94
	v_permlane16_swap_b32_e32 v93, v95
	v_permlane16_swap_b32_e32 v84, v86
	v_permlane16_swap_b32_e32 v85, v87
	global_store_dwordx4 v[226:227], v[92:95], off
	global_store_dwordx4 v[234:235], v[84:87], off
	v_lshl_add_u64 v[226:227], v[226:227], 0, s[82:83]
	v_lshl_add_u64 v[234:235], v[226:227], 0, s[88:89]
	v_pk_mul_f32 v[76:77], v[76:77], v[158:159] op_sel:[0,1] op_sel_hi:[1,1]
	v_pk_mul_f32 v[78:79], v[78:79], v[158:159] op_sel:[0,1] op_sel_hi:[1,1]
	v_pk_mul_f32 v[72:73], v[72:73], v[158:159] op_sel:[0,1] op_sel_hi:[1,1]
	v_pk_mul_f32 v[74:75], v[74:75], v[158:159] op_sel:[0,1] op_sel_hi:[1,1]
	v_pk_mul_f32 v[68:69], v[68:69], v[158:159] op_sel:[0,1] op_sel_hi:[1,1]
	v_pk_mul_f32 v[70:71], v[70:71], v[158:159] op_sel:[0,1] op_sel_hi:[1,1]
	v_pk_mul_f32 v[64:65], v[64:65], v[158:159] op_sel:[0,1] op_sel_hi:[1,1]
	v_pk_mul_f32 v[66:67], v[66:67], v[158:159] op_sel:[0,1] op_sel_hi:[1,1]
	s_and_b64 vcc, exec, s[14:15]
	s_cbranch_vccz .Lkq_norope_3
	v_mul_f32_e32 v142, v72, v203
	v_mul_f32_e32 v233, v76, v203
	v_fma_f32 v76, v76, v202, -v142
	v_fma_f32 v72, v72, v202, v233
	v_mul_f32_e32 v238, v73, v205
	v_mul_f32_e32 v239, v77, v205
	v_fma_f32 v77, v77, v204, -v238
	v_fma_f32 v73, v73, v204, v239
	v_mul_f32_e32 v142, v74, v207
	v_mul_f32_e32 v233, v78, v207
	v_fma_f32 v78, v78, v206, -v142
	v_fma_f32 v74, v74, v206, v233
	v_mul_f32_e32 v238, v75, v209
	v_mul_f32_e32 v239, v79, v209
	v_fma_f32 v79, v79, v208, -v238
	v_fma_f32 v75, v75, v208, v239
	v_mul_f32_e32 v142, v64, v203
	v_mul_f32_e32 v233, v68, v203
	v_fma_f32 v68, v68, v202, -v142
	v_fma_f32 v64, v64, v202, v233
	v_mul_f32_e32 v238, v65, v205
	v_mul_f32_e32 v239, v69, v205
	v_fma_f32 v69, v69, v204, -v238
	v_fma_f32 v65, v65, v204, v239
	v_mul_f32_e32 v142, v66, v207
	v_mul_f32_e32 v233, v70, v207
	v_fma_f32 v70, v70, v206, -v142
	v_fma_f32 v66, v66, v206, v233
	v_mul_f32_e32 v238, v67, v209
	v_mul_f32_e32 v239, v71, v209
	v_fma_f32 v71, v71, v208, -v238
	v_fma_f32 v67, v67, v208, v239
.Lkq_norope_3:
	v_pk_mul_f32 v[76:77], v[76:77], v[236:237] op_sel_hi:[1,0]
	v_pk_mul_f32 v[78:79], v[78:79], v[236:237] op_sel_hi:[1,0]
	v_pk_mul_f32 v[72:73], v[72:73], v[236:237] op_sel_hi:[1,0]
	v_pk_mul_f32 v[74:75], v[74:75], v[236:237] op_sel_hi:[1,0]
	v_pk_mul_f32 v[68:69], v[68:69], v[236:237] op_sel_hi:[1,0]
	v_pk_mul_f32 v[70:71], v[70:71], v[236:237] op_sel_hi:[1,0]
	v_pk_mul_f32 v[64:65], v[64:65], v[236:237] op_sel_hi:[1,0]
	v_pk_mul_f32 v[66:67], v[66:67], v[236:237] op_sel_hi:[1,0]
	v_cvt_pk_bf16_f32 v76, v76, v77
	v_cvt_pk_bf16_f32 v77, v78, v79
	v_cvt_pk_bf16_f32 v78, v72, v73
	v_cvt_pk_bf16_f32 v79, v74, v75
	v_cvt_pk_bf16_f32 v68, v68, v69
	v_cvt_pk_bf16_f32 v69, v70, v71
	v_cvt_pk_bf16_f32 v70, v64, v65
	v_cvt_pk_bf16_f32 v71, v66, v67
	s_nop 1
	v_permlane16_swap_b32_e32 v76, v78
	v_permlane16_swap_b32_e32 v77, v79
	v_permlane16_swap_b32_e32 v68, v70
	v_permlane16_swap_b32_e32 v69, v71
	global_store_dwordx4 v[226:227], v[76:79], off
	global_store_dwordx4 v[234:235], v[68:71], off
	v_lshl_add_u64 v[226:227], v[226:227], 0, s[86:87]
	v_lshl_add_u64 v[234:235], v[226:227], 0, s[88:89]
	v_pk_mul_f32 v[60:61], v[60:61], v[160:161] op_sel:[0,0] op_sel_hi:[1,0]
	v_pk_mul_f32 v[62:63], v[62:63], v[160:161] op_sel:[0,0] op_sel_hi:[1,0]
	v_pk_mul_f32 v[56:57], v[56:57], v[160:161] op_sel:[0,0] op_sel_hi:[1,0]
	v_pk_mul_f32 v[58:59], v[58:59], v[160:161] op_sel:[0,0] op_sel_hi:[1,0]
	v_pk_mul_f32 v[52:53], v[52:53], v[160:161] op_sel:[0,0] op_sel_hi:[1,0]
	v_pk_mul_f32 v[54:55], v[54:55], v[160:161] op_sel:[0,0] op_sel_hi:[1,0]
	v_pk_mul_f32 v[48:49], v[48:49], v[160:161] op_sel:[0,0] op_sel_hi:[1,0]
	v_pk_mul_f32 v[50:51], v[50:51], v[160:161] op_sel:[0,0] op_sel_hi:[1,0]
	s_and_b64 vcc, exec, s[14:15]
	s_cbranch_vccz .Lkq_norope_4
	v_mul_f32_e32 v142, v56, v211
	v_mul_f32_e32 v233, v60, v211
	v_fma_f32 v60, v60, v210, -v142
	v_fma_f32 v56, v56, v210, v233
	v_mul_f32_e32 v238, v57, v213
	v_mul_f32_e32 v239, v61, v213
	v_fma_f32 v61, v61, v212, -v238
	v_fma_f32 v57, v57, v212, v239
	v_mul_f32_e32 v142, v58, v215
	v_mul_f32_e32 v233, v62, v215
	v_fma_f32 v62, v62, v214, -v142
	v_fma_f32 v58, v58, v214, v233
	v_mul_f32_e32 v238, v59, v217
	v_mul_f32_e32 v239, v63, v217
	v_fma_f32 v63, v63, v216, -v238
	v_fma_f32 v59, v59, v216, v239
	v_mul_f32_e32 v142, v48, v211
	v_mul_f32_e32 v233, v52, v211
	v_fma_f32 v52, v52, v210, -v142
	v_fma_f32 v48, v48, v210, v233
	v_mul_f32_e32 v238, v49, v213
	v_mul_f32_e32 v239, v53, v213
	v_fma_f32 v53, v53, v212, -v238
	v_fma_f32 v49, v49, v212, v239
	v_mul_f32_e32 v142, v50, v215
	v_mul_f32_e32 v233, v54, v215
	v_fma_f32 v54, v54, v214, -v142
	v_fma_f32 v50, v50, v214, v233
	v_mul_f32_e32 v238, v51, v217
	v_mul_f32_e32 v239, v55, v217
	v_fma_f32 v55, v55, v216, -v238
	v_fma_f32 v51, v51, v216, v239
.Lkq_norope_4:
	v_pk_mul_f32 v[60:61], v[60:61], v[236:237] op_sel_hi:[1,0]
	v_pk_mul_f32 v[62:63], v[62:63], v[236:237] op_sel_hi:[1,0]
	v_pk_mul_f32 v[56:57], v[56:57], v[236:237] op_sel_hi:[1,0]
	v_pk_mul_f32 v[58:59], v[58:59], v[236:237] op_sel_hi:[1,0]
	v_pk_mul_f32 v[52:53], v[52:53], v[236:237] op_sel_hi:[1,0]
	v_pk_mul_f32 v[54:55], v[54:55], v[236:237] op_sel_hi:[1,0]
	v_pk_mul_f32 v[48:49], v[48:49], v[236:237] op_sel_hi:[1,0]
	v_pk_mul_f32 v[50:51], v[50:51], v[236:237] op_sel_hi:[1,0]
	v_cvt_pk_bf16_f32 v60, v60, v61
	v_cvt_pk_bf16_f32 v61, v62, v63
	v_cvt_pk_bf16_f32 v62, v56, v57
	v_cvt_pk_bf16_f32 v63, v58, v59
	v_cvt_pk_bf16_f32 v52, v52, v53
	v_cvt_pk_bf16_f32 v53, v54, v55
	v_cvt_pk_bf16_f32 v54, v48, v49
	v_cvt_pk_bf16_f32 v55, v50, v51
	s_nop 1
	v_permlane16_swap_b32_e32 v60, v62
	v_permlane16_swap_b32_e32 v61, v63
	v_permlane16_swap_b32_e32 v52, v54
	v_permlane16_swap_b32_e32 v53, v55
	global_store_dwordx4 v[226:227], v[60:63], off
	global_store_dwordx4 v[234:235], v[52:55], off
	v_lshl_add_u64 v[226:227], v[226:227], 0, s[82:83]
	v_lshl_add_u64 v[234:235], v[226:227], 0, s[88:89]
	v_pk_mul_f32 v[44:45], v[44:45], v[160:161] op_sel:[0,1] op_sel_hi:[1,1]
	v_pk_mul_f32 v[46:47], v[46:47], v[160:161] op_sel:[0,1] op_sel_hi:[1,1]
	v_pk_mul_f32 v[40:41], v[40:41], v[160:161] op_sel:[0,1] op_sel_hi:[1,1]
	v_pk_mul_f32 v[42:43], v[42:43], v[160:161] op_sel:[0,1] op_sel_hi:[1,1]
	v_pk_mul_f32 v[36:37], v[36:37], v[160:161] op_sel:[0,1] op_sel_hi:[1,1]
	v_pk_mul_f32 v[38:39], v[38:39], v[160:161] op_sel:[0,1] op_sel_hi:[1,1]
	v_pk_mul_f32 v[32:33], v[32:33], v[160:161] op_sel:[0,1] op_sel_hi:[1,1]
	v_pk_mul_f32 v[34:35], v[34:35], v[160:161] op_sel:[0,1] op_sel_hi:[1,1]
	s_and_b64 vcc, exec, s[14:15]
	s_cbranch_vccz .Lkq_norope_5
	v_mul_f32_e32 v142, v40, v219
	v_mul_f32_e32 v233, v44, v219
	v_fma_f32 v44, v44, v218, -v142
	v_fma_f32 v40, v40, v218, v233
	v_mul_f32_e32 v238, v41, v221
	v_mul_f32_e32 v239, v45, v221
	v_fma_f32 v45, v45, v220, -v238
	v_fma_f32 v41, v41, v220, v239
	v_mul_f32_e32 v142, v42, v121
	v_mul_f32_e32 v233, v46, v121
	v_fma_f32 v46, v46, v120, -v142
	v_fma_f32 v42, v42, v120, v233
	v_mul_f32_e32 v238, v43, v123
	v_mul_f32_e32 v239, v47, v123
	v_fma_f32 v47, v47, v122, -v238
	v_fma_f32 v43, v43, v122, v239
	v_mul_f32_e32 v142, v32, v219
	v_mul_f32_e32 v233, v36, v219
	v_fma_f32 v36, v36, v218, -v142
	v_fma_f32 v32, v32, v218, v233
	v_mul_f32_e32 v238, v33, v221
	v_mul_f32_e32 v239, v37, v221
	v_fma_f32 v37, v37, v220, -v238
	v_fma_f32 v33, v33, v220, v239
	v_mul_f32_e32 v142, v34, v121
	v_mul_f32_e32 v233, v38, v121
	v_fma_f32 v38, v38, v120, -v142
	v_fma_f32 v34, v34, v120, v233
	v_mul_f32_e32 v238, v35, v123
	v_mul_f32_e32 v239, v39, v123
	v_fma_f32 v39, v39, v122, -v238
	v_fma_f32 v35, v35, v122, v239
.Lkq_norope_5:
	v_pk_mul_f32 v[44:45], v[44:45], v[236:237] op_sel_hi:[1,0]
	v_pk_mul_f32 v[46:47], v[46:47], v[236:237] op_sel_hi:[1,0]
	v_pk_mul_f32 v[40:41], v[40:41], v[236:237] op_sel_hi:[1,0]
	v_pk_mul_f32 v[42:43], v[42:43], v[236:237] op_sel_hi:[1,0]
	v_pk_mul_f32 v[36:37], v[36:37], v[236:237] op_sel_hi:[1,0]
	v_pk_mul_f32 v[38:39], v[38:39], v[236:237] op_sel_hi:[1,0]
	v_pk_mul_f32 v[32:33], v[32:33], v[236:237] op_sel_hi:[1,0]
	v_pk_mul_f32 v[34:35], v[34:35], v[236:237] op_sel_hi:[1,0]
	v_cvt_pk_bf16_f32 v44, v44, v45
	v_cvt_pk_bf16_f32 v45, v46, v47
	v_cvt_pk_bf16_f32 v46, v40, v41
	v_cvt_pk_bf16_f32 v47, v42, v43
	v_cvt_pk_bf16_f32 v36, v36, v37
	v_cvt_pk_bf16_f32 v37, v38, v39
	v_cvt_pk_bf16_f32 v38, v32, v33
	v_cvt_pk_bf16_f32 v39, v34, v35
	s_nop 1
	v_permlane16_swap_b32_e32 v44, v46
	v_permlane16_swap_b32_e32 v45, v47
	v_permlane16_swap_b32_e32 v36, v38
	v_permlane16_swap_b32_e32 v37, v39
	global_store_dwordx4 v[226:227], v[44:47], off
	global_store_dwordx4 v[234:235], v[36:39], off
	v_lshl_add_u64 v[226:227], v[226:227], 0, s[82:83]
	v_lshl_add_u64 v[234:235], v[226:227], 0, s[88:89]
	v_pk_mul_f32 v[28:29], v[28:29], v[162:163] op_sel:[0,0] op_sel_hi:[1,0]
	v_pk_mul_f32 v[30:31], v[30:31], v[162:163] op_sel:[0,0] op_sel_hi:[1,0]
	v_pk_mul_f32 v[24:25], v[24:25], v[162:163] op_sel:[0,0] op_sel_hi:[1,0]
	v_pk_mul_f32 v[26:27], v[26:27], v[162:163] op_sel:[0,0] op_sel_hi:[1,0]
	v_pk_mul_f32 v[20:21], v[20:21], v[162:163] op_sel:[0,0] op_sel_hi:[1,0]
	v_pk_mul_f32 v[22:23], v[22:23], v[162:163] op_sel:[0,0] op_sel_hi:[1,0]
	v_pk_mul_f32 v[16:17], v[16:17], v[162:163] op_sel:[0,0] op_sel_hi:[1,0]
	v_pk_mul_f32 v[18:19], v[18:19], v[162:163] op_sel:[0,0] op_sel_hi:[1,0]
	s_and_b64 vcc, exec, s[14:15]
	s_cbranch_vccz .Lkq_norope_6
	v_mul_f32_e32 v142, v24, v125
	v_mul_f32_e32 v233, v28, v125
	v_fma_f32 v28, v28, v124, -v142
	v_fma_f32 v24, v24, v124, v233
	v_mul_f32_e32 v238, v25, v127
	v_mul_f32_e32 v239, v29, v127
	v_fma_f32 v29, v29, v126, -v238
	v_fma_f32 v25, v25, v126, v239
	v_mul_f32_e32 v142, v26, v165
	v_mul_f32_e32 v233, v30, v165
	v_fma_f32 v30, v30, v164, -v142
	v_fma_f32 v26, v26, v164, v233
	v_mul_f32_e32 v238, v27, v167
	v_mul_f32_e32 v239, v31, v167
	v_fma_f32 v31, v31, v166, -v238
	v_fma_f32 v27, v27, v166, v239
	v_mul_f32_e32 v142, v16, v125
	v_mul_f32_e32 v233, v20, v125
	v_fma_f32 v20, v20, v124, -v142
	v_fma_f32 v16, v16, v124, v233
	v_mul_f32_e32 v238, v17, v127
	v_mul_f32_e32 v239, v21, v127
	v_fma_f32 v21, v21, v126, -v238
	v_fma_f32 v17, v17, v126, v239
	v_mul_f32_e32 v142, v18, v165
	v_mul_f32_e32 v233, v22, v165
	v_fma_f32 v22, v22, v164, -v142
	v_fma_f32 v18, v18, v164, v233
	v_mul_f32_e32 v238, v19, v167
	v_mul_f32_e32 v239, v23, v167
	v_fma_f32 v23, v23, v166, -v238
	v_fma_f32 v19, v19, v166, v239
.Lkq_norope_6:
	v_pk_mul_f32 v[28:29], v[28:29], v[236:237] op_sel_hi:[1,0]
	v_pk_mul_f32 v[30:31], v[30:31], v[236:237] op_sel_hi:[1,0]
	v_pk_mul_f32 v[24:25], v[24:25], v[236:237] op_sel_hi:[1,0]
	v_pk_mul_f32 v[26:27], v[26:27], v[236:237] op_sel_hi:[1,0]
	v_pk_mul_f32 v[20:21], v[20:21], v[236:237] op_sel_hi:[1,0]
	v_pk_mul_f32 v[22:23], v[22:23], v[236:237] op_sel_hi:[1,0]
	v_pk_mul_f32 v[16:17], v[16:17], v[236:237] op_sel_hi:[1,0]
	v_pk_mul_f32 v[18:19], v[18:19], v[236:237] op_sel_hi:[1,0]
	v_cvt_pk_bf16_f32 v28, v28, v29
	v_cvt_pk_bf16_f32 v29, v30, v31
	v_cvt_pk_bf16_f32 v30, v24, v25
	v_cvt_pk_bf16_f32 v31, v26, v27
	v_cvt_pk_bf16_f32 v20, v20, v21
	v_cvt_pk_bf16_f32 v21, v22, v23
	v_cvt_pk_bf16_f32 v22, v16, v17
	v_cvt_pk_bf16_f32 v23, v18, v19
	s_nop 1
	v_permlane16_swap_b32_e32 v28, v30
	v_permlane16_swap_b32_e32 v29, v31
	v_permlane16_swap_b32_e32 v20, v22
	v_permlane16_swap_b32_e32 v21, v23
	global_store_dwordx4 v[226:227], v[28:31], off
	global_store_dwordx4 v[234:235], v[20:23], off
	v_lshl_add_u64 v[226:227], v[226:227], 0, s[82:83]
	v_lshl_add_u64 v[234:235], v[226:227], 0, s[88:89]
	v_pk_mul_f32 v[12:13], v[12:13], v[162:163] op_sel:[0,1] op_sel_hi:[1,1]
	v_pk_mul_f32 v[14:15], v[14:15], v[162:163] op_sel:[0,1] op_sel_hi:[1,1]
	v_pk_mul_f32 v[8:9], v[8:9], v[162:163] op_sel:[0,1] op_sel_hi:[1,1]
	v_pk_mul_f32 v[10:11], v[10:11], v[162:163] op_sel:[0,1] op_sel_hi:[1,1]
	v_pk_mul_f32 v[4:5], v[4:5], v[162:163] op_sel:[0,1] op_sel_hi:[1,1]
	v_pk_mul_f32 v[6:7], v[6:7], v[162:163] op_sel:[0,1] op_sel_hi:[1,1]
	v_pk_mul_f32 v[0:1], v[0:1], v[162:163] op_sel:[0,1] op_sel_hi:[1,1]
	v_pk_mul_f32 v[2:3], v[2:3], v[162:163] op_sel:[0,1] op_sel_hi:[1,1]
	s_and_b64 vcc, exec, s[14:15]
	s_cbranch_vccz .Lkq_norope_7
	v_mul_f32_e32 v142, v8, v223
	v_mul_f32_e32 v233, v12, v223
	v_fma_f32 v12, v12, v222, -v142
	v_fma_f32 v8, v8, v222, v233
	v_mul_f32_e32 v238, v9, v225
	v_mul_f32_e32 v239, v13, v225
	v_fma_f32 v13, v13, v224, -v238
	v_fma_f32 v9, v9, v224, v239
	v_mul_f32_e32 v142, v10, v229
	v_mul_f32_e32 v233, v14, v229
	v_fma_f32 v14, v14, v228, -v142
	v_fma_f32 v10, v10, v228, v233
	v_mul_f32_e32 v238, v11, v231
	v_mul_f32_e32 v239, v15, v231
	v_fma_f32 v15, v15, v230, -v238
	v_fma_f32 v11, v11, v230, v239
	v_mul_f32_e32 v142, v0, v223
	v_mul_f32_e32 v233, v4, v223
	v_fma_f32 v4, v4, v222, -v142
	v_fma_f32 v0, v0, v222, v233
	v_mul_f32_e32 v238, v1, v225
	v_mul_f32_e32 v239, v5, v225
	v_fma_f32 v5, v5, v224, -v238
	v_fma_f32 v1, v1, v224, v239
	v_mul_f32_e32 v142, v2, v229
	v_mul_f32_e32 v233, v6, v229
	v_fma_f32 v6, v6, v228, -v142
	v_fma_f32 v2, v2, v228, v233
	v_mul_f32_e32 v238, v3, v231
	v_mul_f32_e32 v239, v7, v231
	v_fma_f32 v7, v7, v230, -v238
	v_fma_f32 v3, v3, v230, v239
.Lkq_norope_7:
	v_pk_mul_f32 v[12:13], v[12:13], v[236:237] op_sel_hi:[1,0]
	v_pk_mul_f32 v[14:15], v[14:15], v[236:237] op_sel_hi:[1,0]
	v_pk_mul_f32 v[8:9], v[8:9], v[236:237] op_sel_hi:[1,0]
	v_pk_mul_f32 v[10:11], v[10:11], v[236:237] op_sel_hi:[1,0]
	v_pk_mul_f32 v[4:5], v[4:5], v[236:237] op_sel_hi:[1,0]
	v_pk_mul_f32 v[6:7], v[6:7], v[236:237] op_sel_hi:[1,0]
	v_pk_mul_f32 v[0:1], v[0:1], v[236:237] op_sel_hi:[1,0]
	v_pk_mul_f32 v[2:3], v[2:3], v[236:237] op_sel_hi:[1,0]
	v_cvt_pk_bf16_f32 v12, v12, v13
	v_cvt_pk_bf16_f32 v13, v14, v15
	v_cvt_pk_bf16_f32 v14, v8, v9
	v_cvt_pk_bf16_f32 v15, v10, v11
	v_cvt_pk_bf16_f32 v4, v4, v5
	v_cvt_pk_bf16_f32 v5, v6, v7
	v_cvt_pk_bf16_f32 v6, v0, v1
	v_cvt_pk_bf16_f32 v7, v2, v3
	s_nop 1
	v_permlane16_swap_b32_e32 v12, v14
	v_permlane16_swap_b32_e32 v13, v15
	v_permlane16_swap_b32_e32 v4, v6
	v_permlane16_swap_b32_e32 v5, v7
	global_store_dwordx4 v[226:227], v[12:15], off
	global_store_dwordx4 v[234:235], v[4:7], off
	s_branch .LBB0_847
